# P3 and P6 epilogues: gate/partial/residual loads batched with counted waits (P3 accumulator map from its K-loop); on top of the pass-C XCD remap, GLA A1 pipelining, P4 epilogue, P2a barrier early writ
# speedup vs baseline: 1.0196x; 1.0060x over previous
; __device__ __forceinline__ void unpack8(const u32x4 w, float (&f)[8]) { f[0] = bflo(w.x); f[1] = bfhi(w.x); f[2] = bflo(w.y); f[3] = bfhi(w.y); f[4] = bflo(w.z); f[5] = bfhi(w.z); f[6] = bflo(w.w); f[7] = bfhi(w.w); }
; __device__ __forceinline__ u32x4 pack8(const float (&f)[8]) { u32x4 w; w.x = cvt_pk_bf16(f[0], f[1]); w.y = cvt_pk_bf16(f[2], f[3]); w.z = cvt_pk_bf16(f[4], f[5]); w.w = cvt_pk_bf16(f[6], f[7]); return w; }
;     __device__ __forceinline__ void operator()(const f32x4 (&acc)[2][2][4][2], const Unit& u, int wr, int wc, int fr, int fq) const {
;         const int row0 = u.pm * BM + wr * 64 + fr, col0 = u.pn * BM + wc * 32 + 8 * fq;
; #pragma unroll
;         for (int ai = 0; ai < 2; ++ai)
; #pragma unroll
;             for (int m = 0; m < 4; ++m) { const size_t idx = (size_t)(row0 + ai * HALF + m * 16) * 1024 + col0;
; #pragma unroll
;                 for (int bj = 0; bj < 2; ++bj) { const f32x4 v0 = acc[ai][bj][m][0], v1 = acc[ai][bj][m][1];
;                     float f[8] = {v0[0], v0[1], v0[2], v0[3], v1[0], v1[1], v1[2], v1[3]}; float g[8];
;                     unpack8(__builtin_nontemporal_load((const u32x4*)(gate + idx + bj * HALF)), g);
; #pragma unroll
;                     for (int e = 0; e < 8; ++e) f[e] *= g[e];
;                     if (!FIRST) { float p[8]; unpack8(*(const u32x4*)(merged + idx + bj * HALF), p);
; #pragma unroll
;                         for (int e = 0; e < 8; ++e) f[e] += p[e]; }
;                     *(u32x4*)(merged + idx + bj * HALF) = pack8(f); } }
;     __device__ __forceinline__ void operator()(const f32x4 (&acc)[2][2][4][2], const Unit& u, int wr, int wc, int fr, int fq) const {
;         if (u.pm < 128) e0(acc, u, wr, wc, fr, fq); else { const Unit v{u.pm - 128, u.pn - 4}; e1(acc, v, wr, wc, fr, fq); }
.LBB0_566:
	s_and_b32 s98, s44, 0x7f
	s_and_b32 s99, s45, 3
	s_cmpk_gt_i32 s44, 0x7f
	s_cselect_b32 s100, s14, s12
	s_cselect_b32 s101, s15, s13
	v_lshl_add_u32 v244, s98, 8, v152
	v_lshl_or_b32 v242, s99, 8, v154
	v_lshl_add_u32 v244, v244, 10, v242
	v_lshlrev_b32_e32 v244, 1, v244
	v_mov_b32_e32 v242, v244
	v_mov_b32_e32 v243, v244
	s_cbranch_scc1 .Lp3_second
	global_load_dwordx4 v[160:163], v244, s[100:101] nt
	global_load_dwordx4 v[164:167], v244, s[100:101] offset:256 nt
	v_add_u32_e32 v244, 0x8000, v244
	global_load_dwordx4 v[168:171], v244, s[100:101] nt
	global_load_dwordx4 v[172:175], v244, s[100:101] offset:256 nt
	v_add_u32_e32 v244, 0x8000, v244
	global_load_dwordx4 v[176:179], v244, s[100:101] nt
	global_load_dwordx4 v[180:183], v244, s[100:101] offset:256 nt
	v_add_u32_e32 v244, 0x8000, v244
	global_load_dwordx4 v[184:187], v244, s[100:101] nt
	global_load_dwordx4 v[188:191], v244, s[100:101] offset:256 nt
	v_add_u32_e32 v244, 0x28000, v244
	global_load_dwordx4 v[192:195], v244, s[100:101] nt
	global_load_dwordx4 v[196:199], v244, s[100:101] offset:256 nt
	v_add_u32_e32 v244, 0x8000, v244
	global_load_dwordx4 v[206:209], v244, s[100:101] nt
	global_load_dwordx4 v[210:213], v244, s[100:101] offset:256 nt
	v_add_u32_e32 v244, 0x8000, v244
	global_load_dwordx4 v[214:217], v244, s[100:101] nt
	global_load_dwordx4 v[218:221], v244, s[100:101] offset:256 nt
	v_add_u32_e32 v244, 0x8000, v244
	global_load_dwordx4 v[222:225], v244, s[100:101] nt
	global_load_dwordx4 v[226:229], v244, s[100:101] offset:256 nt
	s_waitcnt vmcnt(14)
	v_lshlrev_b32_e32 v128, 16, v160
	v_and_b32_e32 v129, 0xffff0000, v160
	v_lshlrev_b32_e32 v130, 16, v161
	v_and_b32_e32 v131, 0xffff0000, v161
	v_lshlrev_b32_e32 v230, 16, v162
	v_and_b32_e32 v231, 0xffff0000, v162
	v_lshlrev_b32_e32 v232, 16, v163
	v_and_b32_e32 v233, 0xffff0000, v163
	v_mul_f32_e32 v124, v124, v128
	v_mul_f32_e32 v125, v125, v129
	v_mul_f32_e32 v126, v126, v130
	v_mul_f32_e32 v127, v127, v131
	v_mul_f32_e32 v120, v120, v230
	v_mul_f32_e32 v121, v121, v231
	v_mul_f32_e32 v122, v122, v232
	v_mul_f32_e32 v123, v123, v233
	v_cvt_pk_bf16_f32 v160, v124, v125
	v_cvt_pk_bf16_f32 v161, v126, v127
	v_cvt_pk_bf16_f32 v162, v120, v121
	v_cvt_pk_bf16_f32 v163, v122, v123
	global_store_dwordx4 v243, v[160:163], s[10:11]
	v_lshlrev_b32_e32 v128, 16, v164
	v_and_b32_e32 v129, 0xffff0000, v164
	v_lshlrev_b32_e32 v130, 16, v165
	v_and_b32_e32 v131, 0xffff0000, v165
	v_lshlrev_b32_e32 v230, 16, v166
	v_and_b32_e32 v231, 0xffff0000, v166
	v_lshlrev_b32_e32 v232, 16, v167
	v_and_b32_e32 v233, 0xffff0000, v167
	v_mul_f32_e32 v112, v112, v128
	v_mul_f32_e32 v113, v113, v129
	v_mul_f32_e32 v114, v114, v130
	v_mul_f32_e32 v115, v115, v131
	v_mul_f32_e32 v104, v104, v230
	v_mul_f32_e32 v105, v105, v231
	v_mul_f32_e32 v106, v106, v232
	v_mul_f32_e32 v107, v107, v233
	v_cvt_pk_bf16_f32 v164, v112, v113
	v_cvt_pk_bf16_f32 v165, v114, v115
	v_cvt_pk_bf16_f32 v166, v104, v105
	v_cvt_pk_bf16_f32 v167, v106, v107
	global_store_dwordx4 v243, v[164:167], s[10:11] offset:256
	v_add_u32_e32 v243, 0x8000, v243
	s_waitcnt vmcnt(14)
	v_lshlrev_b32_e32 v128, 16, v168
	v_and_b32_e32 v129, 0xffff0000, v168
	v_lshlrev_b32_e32 v130, 16, v169
	v_and_b32_e32 v131, 0xffff0000, v169
	v_lshlrev_b32_e32 v230, 16, v170
	v_and_b32_e32 v231, 0xffff0000, v170
	v_lshlrev_b32_e32 v232, 16, v171
	v_and_b32_e32 v233, 0xffff0000, v171
	v_mul_f32_e32 v116, v116, v128
	v_mul_f32_e32 v117, v117, v129
	v_mul_f32_e32 v118, v118, v130
	v_mul_f32_e32 v119, v119, v131
	v_mul_f32_e32 v108, v108, v230
	v_mul_f32_e32 v109, v109, v231
	v_mul_f32_e32 v110, v110, v232
	v_mul_f32_e32 v111, v111, v233
	v_cvt_pk_bf16_f32 v168, v116, v117
	v_cvt_pk_bf16_f32 v169, v118, v119
	v_cvt_pk_bf16_f32 v170, v108, v109
	v_cvt_pk_bf16_f32 v171, v110, v111
	global_store_dwordx4 v243, v[168:171], s[10:11]
	v_lshlrev_b32_e32 v128, 16, v172
	v_and_b32_e32 v129, 0xffff0000, v172
	v_lshlrev_b32_e32 v130, 16, v173
	v_and_b32_e32 v131, 0xffff0000, v173
	v_lshlrev_b32_e32 v230, 16, v174
	v_and_b32_e32 v231, 0xffff0000, v174
	v_lshlrev_b32_e32 v232, 16, v175
	v_and_b32_e32 v233, 0xffff0000, v175
	v_mul_f32_e32 v96, v96, v128
	v_mul_f32_e32 v97, v97, v129
	v_mul_f32_e32 v98, v98, v130
	v_mul_f32_e32 v99, v99, v131
	v_mul_f32_e32 v88, v88, v230
	v_mul_f32_e32 v89, v89, v231
	v_mul_f32_e32 v90, v90, v232
	v_mul_f32_e32 v91, v91, v233
	v_cvt_pk_bf16_f32 v172, v96, v97
	v_cvt_pk_bf16_f32 v173, v98, v99
	v_cvt_pk_bf16_f32 v174, v88, v89
	v_cvt_pk_bf16_f32 v175, v90, v91
	global_store_dwordx4 v243, v[172:175], s[10:11] offset:256
	v_add_u32_e32 v243, 0x8000, v243
	s_waitcnt vmcnt(14)
	v_lshlrev_b32_e32 v128, 16, v176
	v_and_b32_e32 v129, 0xffff0000, v176
	v_lshlrev_b32_e32 v130, 16, v177
	v_and_b32_e32 v131, 0xffff0000, v177
	v_lshlrev_b32_e32 v230, 16, v178
	v_and_b32_e32 v231, 0xffff0000, v178
	v_lshlrev_b32_e32 v232, 16, v179
	v_and_b32_e32 v233, 0xffff0000, v179
	v_mul_f32_e32 v100, v100, v128
	v_mul_f32_e32 v101, v101, v129
	v_mul_f32_e32 v102, v102, v130
	v_mul_f32_e32 v103, v103, v131
	v_mul_f32_e32 v92, v92, v230
	v_mul_f32_e32 v93, v93, v231
	v_mul_f32_e32 v94, v94, v232
	v_mul_f32_e32 v95, v95, v233
	v_cvt_pk_bf16_f32 v176, v100, v101
	v_cvt_pk_bf16_f32 v177, v102, v103
	v_cvt_pk_bf16_f32 v178, v92, v93
	v_cvt_pk_bf16_f32 v179, v94, v95
	global_store_dwordx4 v243, v[176:179], s[10:11]
	v_lshlrev_b32_e32 v128, 16, v180
	v_and_b32_e32 v129, 0xffff0000, v180
	v_lshlrev_b32_e32 v130, 16, v181
	v_and_b32_e32 v131, 0xffff0000, v181
	v_lshlrev_b32_e32 v230, 16, v182
	v_and_b32_e32 v231, 0xffff0000, v182
	v_lshlrev_b32_e32 v232, 16, v183
	v_and_b32_e32 v233, 0xffff0000, v183
	v_mul_f32_e32 v80, v80, v128
	v_mul_f32_e32 v81, v81, v129
	v_mul_f32_e32 v82, v82, v130
	v_mul_f32_e32 v83, v83, v131
	v_mul_f32_e32 v72, v72, v230
	v_mul_f32_e32 v73, v73, v231
	v_mul_f32_e32 v74, v74, v232
	v_mul_f32_e32 v75, v75, v233
	v_cvt_pk_bf16_f32 v180, v80, v81
	v_cvt_pk_bf16_f32 v181, v82, v83
	v_cvt_pk_bf16_f32 v182, v72, v73
	v_cvt_pk_bf16_f32 v183, v74, v75
	global_store_dwordx4 v243, v[180:183], s[10:11] offset:256
	v_add_u32_e32 v243, 0x8000, v243
	s_waitcnt vmcnt(14)
; __device__ __forceinline__ void unpack8(const u32x4 w, float (&f)[8]) { f[0] = bflo(w.x); f[1] = bfhi(w.x); f[2] = bflo(w.y); f[3] = bfhi(w.y); f[4] = bflo(w.z); f[5] = bfhi(w.z); f[6] = bflo(w.w); f[7] = bfhi(w.w); }
; __device__ __forceinline__ u32x4 pack8(const float (&f)[8]) { u32x4 w; w.x = cvt_pk_bf16(f[0], f[1]); w.y = cvt_pk_bf16(f[2], f[3]); w.z = cvt_pk_bf16(f[4], f[5]); w.w = cvt_pk_bf16(f[6], f[7]); return w; }
;     __device__ __forceinline__ void operator()(const f32x4 (&acc)[2][2][4][2], const Unit& u, int wr, int wc, int fr, int fq) const {
;     ...
;             for (int m = 0; m < 4; ++m) { const size_t idx = (size_t)(row0 + ai * HALF + m * 16) * 1024 + col0;
; #pragma unroll
;                 for (int bj = 0; bj < 2; ++bj) { const f32x4 v0 = acc[ai][bj][m][0], v1 = acc[ai][bj][m][1];
;                     float f[8] = {v0[0], v0[1], v0[2], v0[3], v1[0], v1[1], v1[2], v1[3]}; float g[8];
;                     unpack8(__builtin_nontemporal_load((const u32x4*)(gate + idx + bj * HALF)), g);
; #pragma unroll
;                     for (int e = 0; e < 8; ++e) f[e] *= g[e];
;                     if (!FIRST) { float p[8]; unpack8(*(const u32x4*)(merged + idx + bj * HALF), p);
; #pragma unroll
;                         for (int e = 0; e < 8; ++e) f[e] += p[e]; }
;                     *(u32x4*)(merged + idx + bj * HALF) = pack8(f); } }
	v_lshlrev_b32_e32 v128, 16, v184
	v_and_b32_e32 v129, 0xffff0000, v184
	v_lshlrev_b32_e32 v130, 16, v185
	v_and_b32_e32 v131, 0xffff0000, v185
	v_lshlrev_b32_e32 v230, 16, v186
	v_and_b32_e32 v231, 0xffff0000, v186
	v_lshlrev_b32_e32 v232, 16, v187
	v_and_b32_e32 v233, 0xffff0000, v187
	v_mul_f32_e32 v84, v84, v128
	v_mul_f32_e32 v85, v85, v129
	v_mul_f32_e32 v86, v86, v130
	v_mul_f32_e32 v87, v87, v131
	v_mul_f32_e32 v76, v76, v230
	v_mul_f32_e32 v77, v77, v231
	v_mul_f32_e32 v78, v78, v232
	v_mul_f32_e32 v79, v79, v233
	v_cvt_pk_bf16_f32 v184, v84, v85
	v_cvt_pk_bf16_f32 v185, v86, v87
	v_cvt_pk_bf16_f32 v186, v76, v77
	v_cvt_pk_bf16_f32 v187, v78, v79
	global_store_dwordx4 v243, v[184:187], s[10:11]
	v_lshlrev_b32_e32 v128, 16, v188
	v_and_b32_e32 v129, 0xffff0000, v188
	v_lshlrev_b32_e32 v130, 16, v189
	v_and_b32_e32 v131, 0xffff0000, v189
	v_lshlrev_b32_e32 v230, 16, v190
	v_and_b32_e32 v231, 0xffff0000, v190
	v_lshlrev_b32_e32 v232, 16, v191
	v_and_b32_e32 v233, 0xffff0000, v191
	v_mul_f32_e32 v68, v68, v128
	v_mul_f32_e32 v69, v69, v129
	v_mul_f32_e32 v70, v70, v130
	v_mul_f32_e32 v71, v71, v131
	v_mul_f32_e32 v64, v64, v230
	v_mul_f32_e32 v65, v65, v231
	v_mul_f32_e32 v66, v66, v232
	v_mul_f32_e32 v67, v67, v233
	v_cvt_pk_bf16_f32 v188, v68, v69
	v_cvt_pk_bf16_f32 v189, v70, v71
	v_cvt_pk_bf16_f32 v190, v64, v65
	v_cvt_pk_bf16_f32 v191, v66, v67
	global_store_dwordx4 v243, v[188:191], s[10:11] offset:256
	v_add_u32_e32 v243, 0x28000, v243
	s_waitcnt vmcnt(14)
	v_lshlrev_b32_e32 v128, 16, v192
	v_and_b32_e32 v129, 0xffff0000, v192
	v_lshlrev_b32_e32 v130, 16, v193
	v_and_b32_e32 v131, 0xffff0000, v193
	v_lshlrev_b32_e32 v230, 16, v194
	v_and_b32_e32 v231, 0xffff0000, v194
	v_lshlrev_b32_e32 v232, 16, v195
	v_and_b32_e32 v233, 0xffff0000, v195
	v_mul_f32_e32 v60, v60, v128
	v_mul_f32_e32 v61, v61, v129
	v_mul_f32_e32 v62, v62, v130
	v_mul_f32_e32 v63, v63, v131
	v_mul_f32_e32 v56, v56, v230
	v_mul_f32_e32 v57, v57, v231
	v_mul_f32_e32 v58, v58, v232
	v_mul_f32_e32 v59, v59, v233
	v_cvt_pk_bf16_f32 v192, v60, v61
	v_cvt_pk_bf16_f32 v193, v62, v63
	v_cvt_pk_bf16_f32 v194, v56, v57
	v_cvt_pk_bf16_f32 v195, v58, v59
	global_store_dwordx4 v243, v[192:195], s[10:11]
	v_lshlrev_b32_e32 v128, 16, v196
	v_and_b32_e32 v129, 0xffff0000, v196
	v_lshlrev_b32_e32 v130, 16, v197
	v_and_b32_e32 v131, 0xffff0000, v197
	v_lshlrev_b32_e32 v230, 16, v198
	v_and_b32_e32 v231, 0xffff0000, v198
	v_lshlrev_b32_e32 v232, 16, v199
	v_and_b32_e32 v233, 0xffff0000, v199
	v_mul_f32_e32 v48, v48, v128
	v_mul_f32_e32 v49, v49, v129
	v_mul_f32_e32 v50, v50, v130
	v_mul_f32_e32 v51, v51, v131
	v_mul_f32_e32 v40, v40, v230
	v_mul_f32_e32 v41, v41, v231
	v_mul_f32_e32 v42, v42, v232
	v_mul_f32_e32 v43, v43, v233
	v_cvt_pk_bf16_f32 v196, v48, v49
	v_cvt_pk_bf16_f32 v197, v50, v51
	v_cvt_pk_bf16_f32 v198, v40, v41
	v_cvt_pk_bf16_f32 v199, v42, v43
	global_store_dwordx4 v243, v[196:199], s[10:11] offset:256
	v_add_u32_e32 v243, 0x8000, v243
	s_waitcnt vmcnt(14)
	v_lshlrev_b32_e32 v128, 16, v206
	v_and_b32_e32 v129, 0xffff0000, v206
	v_lshlrev_b32_e32 v130, 16, v207
	v_and_b32_e32 v131, 0xffff0000, v207
	v_lshlrev_b32_e32 v230, 16, v208
	v_and_b32_e32 v231, 0xffff0000, v208
	v_lshlrev_b32_e32 v232, 16, v209
	v_and_b32_e32 v233, 0xffff0000, v209
	v_mul_f32_e32 v52, v52, v128
	v_mul_f32_e32 v53, v53, v129
	v_mul_f32_e32 v54, v54, v130
	v_mul_f32_e32 v55, v55, v131
	v_mul_f32_e32 v44, v44, v230
	v_mul_f32_e32 v45, v45, v231
	v_mul_f32_e32 v46, v46, v232
	v_mul_f32_e32 v47, v47, v233
	v_cvt_pk_bf16_f32 v206, v52, v53
	v_cvt_pk_bf16_f32 v207, v54, v55
	v_cvt_pk_bf16_f32 v208, v44, v45
	v_cvt_pk_bf16_f32 v209, v46, v47
	global_store_dwordx4 v243, v[206:209], s[10:11]
	v_lshlrev_b32_e32 v128, 16, v210
	v_and_b32_e32 v129, 0xffff0000, v210
	v_lshlrev_b32_e32 v130, 16, v211
	v_and_b32_e32 v131, 0xffff0000, v211
	v_lshlrev_b32_e32 v230, 16, v212
	v_and_b32_e32 v231, 0xffff0000, v212
	v_lshlrev_b32_e32 v232, 16, v213
	v_and_b32_e32 v233, 0xffff0000, v213
	v_mul_f32_e32 v32, v32, v128
	v_mul_f32_e32 v33, v33, v129
	v_mul_f32_e32 v34, v34, v130
	v_mul_f32_e32 v35, v35, v131
	v_mul_f32_e32 v24, v24, v230
	v_mul_f32_e32 v25, v25, v231
	v_mul_f32_e32 v26, v26, v232
	v_mul_f32_e32 v27, v27, v233
	v_cvt_pk_bf16_f32 v210, v32, v33
	v_cvt_pk_bf16_f32 v211, v34, v35
	v_cvt_pk_bf16_f32 v212, v24, v25
	v_cvt_pk_bf16_f32 v213, v26, v27
	global_store_dwordx4 v243, v[210:213], s[10:11] offset:256
	v_add_u32_e32 v243, 0x8000, v243
	s_waitcnt vmcnt(14)
	v_lshlrev_b32_e32 v128, 16, v214
	v_and_b32_e32 v129, 0xffff0000, v214
	v_lshlrev_b32_e32 v130, 16, v215
	v_and_b32_e32 v131, 0xffff0000, v215
	v_lshlrev_b32_e32 v230, 16, v216
	v_and_b32_e32 v231, 0xffff0000, v216
	v_lshlrev_b32_e32 v232, 16, v217
	v_and_b32_e32 v233, 0xffff0000, v217
	v_mul_f32_e32 v36, v36, v128
	v_mul_f32_e32 v37, v37, v129
	v_mul_f32_e32 v38, v38, v130
	v_mul_f32_e32 v39, v39, v131
	v_mul_f32_e32 v28, v28, v230
	v_mul_f32_e32 v29, v29, v231
	v_mul_f32_e32 v30, v30, v232
	v_mul_f32_e32 v31, v31, v233
	v_cvt_pk_bf16_f32 v214, v36, v37
	v_cvt_pk_bf16_f32 v215, v38, v39
	v_cvt_pk_bf16_f32 v216, v28, v29
	v_cvt_pk_bf16_f32 v217, v30, v31
	global_store_dwordx4 v243, v[214:217], s[10:11]
	v_lshlrev_b32_e32 v128, 16, v218
	v_and_b32_e32 v129, 0xffff0000, v218
	v_lshlrev_b32_e32 v130, 16, v219
	v_and_b32_e32 v131, 0xffff0000, v219
	v_lshlrev_b32_e32 v230, 16, v220
	v_and_b32_e32 v231, 0xffff0000, v220
	v_lshlrev_b32_e32 v232, 16, v221
	v_and_b32_e32 v233, 0xffff0000, v221
	v_mul_f32_e32 v16, v16, v128
	v_mul_f32_e32 v17, v17, v129
	v_mul_f32_e32 v18, v18, v130
	v_mul_f32_e32 v19, v19, v131
	v_mul_f32_e32 v8, v8, v230
	v_mul_f32_e32 v9, v9, v231
	v_mul_f32_e32 v10, v10, v232
	v_mul_f32_e32 v11, v11, v233
	v_cvt_pk_bf16_f32 v218, v16, v17
	v_cvt_pk_bf16_f32 v219, v18, v19
	v_cvt_pk_bf16_f32 v220, v8, v9
	v_cvt_pk_bf16_f32 v221, v10, v11
	global_store_dwordx4 v243, v[218:221], s[10:11] offset:256
	v_add_u32_e32 v243, 0x8000, v243
	s_waitcnt vmcnt(14)
; __device__ __forceinline__ void unpack8(const u32x4 w, float (&f)[8]) { f[0] = bflo(w.x); f[1] = bfhi(w.x); f[2] = bflo(w.y); f[3] = bfhi(w.y); f[4] = bflo(w.z); f[5] = bfhi(w.z); f[6] = bflo(w.w); f[7] = bfhi(w.w); }
; __device__ __forceinline__ u32x4 pack8(const float (&f)[8]) { u32x4 w; w.x = cvt_pk_bf16(f[0], f[1]); w.y = cvt_pk_bf16(f[2], f[3]); w.z = cvt_pk_bf16(f[4], f[5]); w.w = cvt_pk_bf16(f[6], f[7]); return w; }
;     __device__ __forceinline__ void operator()(const f32x4 (&acc)[2][2][4][2], const Unit& u, int wr, int wc, int fr, int fq) const {
;     ...
;             for (int m = 0; m < 4; ++m) { const size_t idx = (size_t)(row0 + ai * HALF + m * 16) * 1024 + col0;
; #pragma unroll
;                 for (int bj = 0; bj < 2; ++bj) { const f32x4 v0 = acc[ai][bj][m][0], v1 = acc[ai][bj][m][1];
;                     float f[8] = {v0[0], v0[1], v0[2], v0[3], v1[0], v1[1], v1[2], v1[3]}; float g[8];
;                     unpack8(__builtin_nontemporal_load((const u32x4*)(gate + idx + bj * HALF)), g);
; #pragma unroll
;                     for (int e = 0; e < 8; ++e) f[e] *= g[e];
;                     if (!FIRST) { float p[8]; unpack8(*(const u32x4*)(merged + idx + bj * HALF), p);
; #pragma unroll
;                         for (int e = 0; e < 8; ++e) f[e] += p[e]; }
;                     *(u32x4*)(merged + idx + bj * HALF) = pack8(f); } }
	v_lshlrev_b32_e32 v128, 16, v222
	v_and_b32_e32 v129, 0xffff0000, v222
	v_lshlrev_b32_e32 v130, 16, v223
	v_and_b32_e32 v131, 0xffff0000, v223
	v_lshlrev_b32_e32 v230, 16, v224
	v_and_b32_e32 v231, 0xffff0000, v224
	v_lshlrev_b32_e32 v232, 16, v225
	v_and_b32_e32 v233, 0xffff0000, v225
	v_mul_f32_e32 v20, v20, v128
	v_mul_f32_e32 v21, v21, v129
	v_mul_f32_e32 v22, v22, v130
	v_mul_f32_e32 v23, v23, v131
	v_mul_f32_e32 v12, v12, v230
	v_mul_f32_e32 v13, v13, v231
	v_mul_f32_e32 v14, v14, v232
	v_mul_f32_e32 v15, v15, v233
	v_cvt_pk_bf16_f32 v222, v20, v21
	v_cvt_pk_bf16_f32 v223, v22, v23
	v_cvt_pk_bf16_f32 v224, v12, v13
	v_cvt_pk_bf16_f32 v225, v14, v15
	global_store_dwordx4 v243, v[222:225], s[10:11]
	v_lshlrev_b32_e32 v128, 16, v226
	v_and_b32_e32 v129, 0xffff0000, v226
	v_lshlrev_b32_e32 v130, 16, v227
	v_and_b32_e32 v131, 0xffff0000, v227
	v_lshlrev_b32_e32 v230, 16, v228
	v_and_b32_e32 v231, 0xffff0000, v228
	v_lshlrev_b32_e32 v232, 16, v229
	v_and_b32_e32 v233, 0xffff0000, v229
	v_mul_f32_e32 v4, v4, v128
	v_mul_f32_e32 v5, v5, v129
	v_mul_f32_e32 v6, v6, v130
	v_mul_f32_e32 v7, v7, v131
	v_mul_f32_e32 v0, v0, v230
	v_mul_f32_e32 v1, v1, v231
	v_mul_f32_e32 v2, v2, v232
	v_mul_f32_e32 v3, v3, v233
	v_cvt_pk_bf16_f32 v226, v4, v5
	v_cvt_pk_bf16_f32 v227, v6, v7
	v_cvt_pk_bf16_f32 v228, v0, v1
	v_cvt_pk_bf16_f32 v229, v2, v3
	global_store_dwordx4 v243, v[226:229], s[10:11] offset:256
	s_branch .Lp3_done
.Lp3_second:
	global_load_dwordx4 v[160:163], v244, s[100:101] nt
	global_load_dwordx4 v[164:167], v244, s[100:101] offset:256 nt
	global_load_dwordx4 v[168:171], v242, s[10:11]
	global_load_dwordx4 v[172:175], v242, s[10:11] offset:256
	v_add_u32_e32 v244, 0x8000, v244
	v_add_u32_e32 v242, 0x8000, v242
	global_load_dwordx4 v[176:179], v244, s[100:101] nt
	global_load_dwordx4 v[180:183], v244, s[100:101] offset:256 nt
	global_load_dwordx4 v[184:187], v242, s[10:11]
	global_load_dwordx4 v[188:191], v242, s[10:11] offset:256
	v_add_u32_e32 v244, 0x8000, v244
	v_add_u32_e32 v242, 0x8000, v242
	global_load_dwordx4 v[192:195], v244, s[100:101] nt
	global_load_dwordx4 v[196:199], v244, s[100:101] offset:256 nt
	global_load_dwordx4 v[206:209], v242, s[10:11]
	global_load_dwordx4 v[210:213], v242, s[10:11] offset:256
	v_add_u32_e32 v244, 0x8000, v244
	v_add_u32_e32 v242, 0x8000, v242
	global_load_dwordx4 v[214:217], v244, s[100:101] nt
	global_load_dwordx4 v[218:221], v244, s[100:101] offset:256 nt
	global_load_dwordx4 v[222:225], v242, s[10:11]
	global_load_dwordx4 v[226:229], v242, s[10:11] offset:256
	v_add_u32_e32 v244, 0x28000, v244
	v_add_u32_e32 v242, 0x28000, v242
	s_waitcnt vmcnt(12)
	v_lshlrev_b32_e32 v128, 16, v160
	v_and_b32_e32 v129, 0xffff0000, v160
	v_lshlrev_b32_e32 v130, 16, v161
	v_and_b32_e32 v131, 0xffff0000, v161
	v_lshlrev_b32_e32 v230, 16, v162
	v_and_b32_e32 v231, 0xffff0000, v162
	v_lshlrev_b32_e32 v232, 16, v163
	v_and_b32_e32 v233, 0xffff0000, v163
	v_lshlrev_b32_e32 v148, 16, v168
	v_and_b32_e32 v149, 0xffff0000, v168
	v_lshlrev_b32_e32 v150, 16, v169
	v_and_b32_e32 v151, 0xffff0000, v169
	v_lshlrev_b32_e32 v200, 16, v170
	v_and_b32_e32 v201, 0xffff0000, v170
	v_lshlrev_b32_e32 v202, 16, v171
	v_and_b32_e32 v203, 0xffff0000, v171
	v_fmac_f32_e32 v148, v124, v128
	v_fmac_f32_e32 v149, v125, v129
	v_fmac_f32_e32 v150, v126, v130
	v_fmac_f32_e32 v151, v127, v131
	v_fmac_f32_e32 v200, v120, v230
	v_fmac_f32_e32 v201, v121, v231
	v_fmac_f32_e32 v202, v122, v232
	v_fmac_f32_e32 v203, v123, v233
	v_cvt_pk_bf16_f32 v160, v148, v149
	v_cvt_pk_bf16_f32 v161, v150, v151
	v_cvt_pk_bf16_f32 v162, v200, v201
	v_cvt_pk_bf16_f32 v163, v202, v203
	global_store_dwordx4 v243, v[160:163], s[10:11]
	v_lshlrev_b32_e32 v128, 16, v164
	v_and_b32_e32 v129, 0xffff0000, v164
	v_lshlrev_b32_e32 v130, 16, v165
	v_and_b32_e32 v131, 0xffff0000, v165
	v_lshlrev_b32_e32 v230, 16, v166
	v_and_b32_e32 v231, 0xffff0000, v166
	v_lshlrev_b32_e32 v232, 16, v167
	v_and_b32_e32 v233, 0xffff0000, v167
	v_lshlrev_b32_e32 v148, 16, v172
	v_and_b32_e32 v149, 0xffff0000, v172
	v_lshlrev_b32_e32 v150, 16, v173
	v_and_b32_e32 v151, 0xffff0000, v173
	v_lshlrev_b32_e32 v200, 16, v174
	v_and_b32_e32 v201, 0xffff0000, v174
	v_lshlrev_b32_e32 v202, 16, v175
	v_and_b32_e32 v203, 0xffff0000, v175
	v_fmac_f32_e32 v148, v112, v128
	v_fmac_f32_e32 v149, v113, v129
	v_fmac_f32_e32 v150, v114, v130
	v_fmac_f32_e32 v151, v115, v131
	v_fmac_f32_e32 v200, v104, v230
	v_fmac_f32_e32 v201, v105, v231
	v_fmac_f32_e32 v202, v106, v232
	v_fmac_f32_e32 v203, v107, v233
	v_cvt_pk_bf16_f32 v164, v148, v149
	v_cvt_pk_bf16_f32 v165, v150, v151
	v_cvt_pk_bf16_f32 v166, v200, v201
	v_cvt_pk_bf16_f32 v167, v202, v203
	global_store_dwordx4 v243, v[164:167], s[10:11] offset:256
	v_add_u32_e32 v243, 0x8000, v243
	global_load_dwordx4 v[160:163], v244, s[100:101] nt
	global_load_dwordx4 v[164:167], v244, s[100:101] offset:256 nt
	global_load_dwordx4 v[168:171], v242, s[10:11]
	global_load_dwordx4 v[172:175], v242, s[10:11] offset:256
	v_add_u32_e32 v244, 0x8000, v244
	v_add_u32_e32 v242, 0x8000, v242
	s_waitcnt vmcnt(14)
; __device__ __forceinline__ void unpack8(const u32x4 w, float (&f)[8]) { f[0] = bflo(w.x); f[1] = bfhi(w.x); f[2] = bflo(w.y); f[3] = bfhi(w.y); f[4] = bflo(w.z); f[5] = bfhi(w.z); f[6] = bflo(w.w); f[7] = bfhi(w.w); }
; __device__ __forceinline__ u32x4 pack8(const float (&f)[8]) { u32x4 w; w.x = cvt_pk_bf16(f[0], f[1]); w.y = cvt_pk_bf16(f[2], f[3]); w.z = cvt_pk_bf16(f[4], f[5]); w.w = cvt_pk_bf16(f[6], f[7]); return w; }
;     __device__ __forceinline__ void operator()(const f32x4 (&acc)[2][2][4][2], const Unit& u, int wr, int wc, int fr, int fq) const {
;     ...
;             for (int m = 0; m < 4; ++m) { const size_t idx = (size_t)(row0 + ai * HALF + m * 16) * 1024 + col0;
; #pragma unroll
;                 for (int bj = 0; bj < 2; ++bj) { const f32x4 v0 = acc[ai][bj][m][0], v1 = acc[ai][bj][m][1];
;                     float f[8] = {v0[0], v0[1], v0[2], v0[3], v1[0], v1[1], v1[2], v1[3]}; float g[8];
;                     unpack8(__builtin_nontemporal_load((const u32x4*)(gate + idx + bj * HALF)), g);
; #pragma unroll
;                     for (int e = 0; e < 8; ++e) f[e] *= g[e];
;                     if (!FIRST) { float p[8]; unpack8(*(const u32x4*)(merged + idx + bj * HALF), p);
; #pragma unroll
;                         for (int e = 0; e < 8; ++e) f[e] += p[e]; }
;                     *(u32x4*)(merged + idx + bj * HALF) = pack8(f); } }
	v_lshlrev_b32_e32 v128, 16, v176
	v_and_b32_e32 v129, 0xffff0000, v176
	v_lshlrev_b32_e32 v130, 16, v177
	v_and_b32_e32 v131, 0xffff0000, v177
	v_lshlrev_b32_e32 v230, 16, v178
	v_and_b32_e32 v231, 0xffff0000, v178
	v_lshlrev_b32_e32 v232, 16, v179
	v_and_b32_e32 v233, 0xffff0000, v179
	v_lshlrev_b32_e32 v148, 16, v184
	v_and_b32_e32 v149, 0xffff0000, v184
	v_lshlrev_b32_e32 v150, 16, v185
	v_and_b32_e32 v151, 0xffff0000, v185
	v_lshlrev_b32_e32 v200, 16, v186
	v_and_b32_e32 v201, 0xffff0000, v186
	v_lshlrev_b32_e32 v202, 16, v187
	v_and_b32_e32 v203, 0xffff0000, v187
	v_fmac_f32_e32 v148, v116, v128
	v_fmac_f32_e32 v149, v117, v129
	v_fmac_f32_e32 v150, v118, v130
	v_fmac_f32_e32 v151, v119, v131
	v_fmac_f32_e32 v200, v108, v230
	v_fmac_f32_e32 v201, v109, v231
	v_fmac_f32_e32 v202, v110, v232
	v_fmac_f32_e32 v203, v111, v233
	v_cvt_pk_bf16_f32 v176, v148, v149
	v_cvt_pk_bf16_f32 v177, v150, v151
	v_cvt_pk_bf16_f32 v178, v200, v201
	v_cvt_pk_bf16_f32 v179, v202, v203
	global_store_dwordx4 v243, v[176:179], s[10:11]
	v_lshlrev_b32_e32 v128, 16, v180
	v_and_b32_e32 v129, 0xffff0000, v180
	v_lshlrev_b32_e32 v130, 16, v181
	v_and_b32_e32 v131, 0xffff0000, v181
	v_lshlrev_b32_e32 v230, 16, v182
	v_and_b32_e32 v231, 0xffff0000, v182
	v_lshlrev_b32_e32 v232, 16, v183
	v_and_b32_e32 v233, 0xffff0000, v183
	v_lshlrev_b32_e32 v148, 16, v188
	v_and_b32_e32 v149, 0xffff0000, v188
	v_lshlrev_b32_e32 v150, 16, v189
	v_and_b32_e32 v151, 0xffff0000, v189
	v_lshlrev_b32_e32 v200, 16, v190
	v_and_b32_e32 v201, 0xffff0000, v190
	v_lshlrev_b32_e32 v202, 16, v191
	v_and_b32_e32 v203, 0xffff0000, v191
	v_fmac_f32_e32 v148, v96, v128
	v_fmac_f32_e32 v149, v97, v129
	v_fmac_f32_e32 v150, v98, v130
	v_fmac_f32_e32 v151, v99, v131
	v_fmac_f32_e32 v200, v88, v230
	v_fmac_f32_e32 v201, v89, v231
	v_fmac_f32_e32 v202, v90, v232
	v_fmac_f32_e32 v203, v91, v233
	v_cvt_pk_bf16_f32 v180, v148, v149
	v_cvt_pk_bf16_f32 v181, v150, v151
	v_cvt_pk_bf16_f32 v182, v200, v201
	v_cvt_pk_bf16_f32 v183, v202, v203
	global_store_dwordx4 v243, v[180:183], s[10:11] offset:256
	v_add_u32_e32 v243, 0x8000, v243
	global_load_dwordx4 v[176:179], v244, s[100:101] nt
	global_load_dwordx4 v[180:183], v244, s[100:101] offset:256 nt
	global_load_dwordx4 v[184:187], v242, s[10:11]
	global_load_dwordx4 v[188:191], v242, s[10:11] offset:256
	v_add_u32_e32 v244, 0x8000, v244
	v_add_u32_e32 v242, 0x8000, v242
	s_waitcnt vmcnt(16)
	v_lshlrev_b32_e32 v128, 16, v192
	v_and_b32_e32 v129, 0xffff0000, v192
	v_lshlrev_b32_e32 v130, 16, v193
	v_and_b32_e32 v131, 0xffff0000, v193
	v_lshlrev_b32_e32 v230, 16, v194
	v_and_b32_e32 v231, 0xffff0000, v194
	v_lshlrev_b32_e32 v232, 16, v195
	v_and_b32_e32 v233, 0xffff0000, v195
	v_lshlrev_b32_e32 v148, 16, v206
	v_and_b32_e32 v149, 0xffff0000, v206
	v_lshlrev_b32_e32 v150, 16, v207
	v_and_b32_e32 v151, 0xffff0000, v207
	v_lshlrev_b32_e32 v200, 16, v208
	v_and_b32_e32 v201, 0xffff0000, v208
	v_lshlrev_b32_e32 v202, 16, v209
	v_and_b32_e32 v203, 0xffff0000, v209
	v_fmac_f32_e32 v148, v100, v128
	v_fmac_f32_e32 v149, v101, v129
	v_fmac_f32_e32 v150, v102, v130
	v_fmac_f32_e32 v151, v103, v131
	v_fmac_f32_e32 v200, v92, v230
	v_fmac_f32_e32 v201, v93, v231
	v_fmac_f32_e32 v202, v94, v232
	v_fmac_f32_e32 v203, v95, v233
	v_cvt_pk_bf16_f32 v192, v148, v149
	v_cvt_pk_bf16_f32 v193, v150, v151
	v_cvt_pk_bf16_f32 v194, v200, v201
	v_cvt_pk_bf16_f32 v195, v202, v203
	global_store_dwordx4 v243, v[192:195], s[10:11]
	v_lshlrev_b32_e32 v128, 16, v196
	v_and_b32_e32 v129, 0xffff0000, v196
	v_lshlrev_b32_e32 v130, 16, v197
	v_and_b32_e32 v131, 0xffff0000, v197
	v_lshlrev_b32_e32 v230, 16, v198
	v_and_b32_e32 v231, 0xffff0000, v198
	v_lshlrev_b32_e32 v232, 16, v199
	v_and_b32_e32 v233, 0xffff0000, v199
	v_lshlrev_b32_e32 v148, 16, v210
	v_and_b32_e32 v149, 0xffff0000, v210
	v_lshlrev_b32_e32 v150, 16, v211
	v_and_b32_e32 v151, 0xffff0000, v211
	v_lshlrev_b32_e32 v200, 16, v212
	v_and_b32_e32 v201, 0xffff0000, v212
	v_lshlrev_b32_e32 v202, 16, v213
	v_and_b32_e32 v203, 0xffff0000, v213
	v_fmac_f32_e32 v148, v80, v128
	v_fmac_f32_e32 v149, v81, v129
	v_fmac_f32_e32 v150, v82, v130
	v_fmac_f32_e32 v151, v83, v131
	v_fmac_f32_e32 v200, v72, v230
	v_fmac_f32_e32 v201, v73, v231
	v_fmac_f32_e32 v202, v74, v232
	v_fmac_f32_e32 v203, v75, v233
	v_cvt_pk_bf16_f32 v196, v148, v149
	v_cvt_pk_bf16_f32 v197, v150, v151
	v_cvt_pk_bf16_f32 v198, v200, v201
	v_cvt_pk_bf16_f32 v199, v202, v203
	global_store_dwordx4 v243, v[196:199], s[10:11] offset:256
	v_add_u32_e32 v243, 0x8000, v243
	global_load_dwordx4 v[192:195], v244, s[100:101] nt
	global_load_dwordx4 v[196:199], v244, s[100:101] offset:256 nt
	global_load_dwordx4 v[206:209], v242, s[10:11]
	global_load_dwordx4 v[210:213], v242, s[10:11] offset:256
	v_add_u32_e32 v244, 0x8000, v244
	v_add_u32_e32 v242, 0x8000, v242
	s_waitcnt vmcnt(18)
; __device__ __forceinline__ void unpack8(const u32x4 w, float (&f)[8]) { f[0] = bflo(w.x); f[1] = bfhi(w.x); f[2] = bflo(w.y); f[3] = bfhi(w.y); f[4] = bflo(w.z); f[5] = bfhi(w.z); f[6] = bflo(w.w); f[7] = bfhi(w.w); }
; __device__ __forceinline__ u32x4 pack8(const float (&f)[8]) { u32x4 w; w.x = cvt_pk_bf16(f[0], f[1]); w.y = cvt_pk_bf16(f[2], f[3]); w.z = cvt_pk_bf16(f[4], f[5]); w.w = cvt_pk_bf16(f[6], f[7]); return w; }
;     __device__ __forceinline__ void operator()(const f32x4 (&acc)[2][2][4][2], const Unit& u, int wr, int wc, int fr, int fq) const {
;     ...
;             for (int m = 0; m < 4; ++m) { const size_t idx = (size_t)(row0 + ai * HALF + m * 16) * 1024 + col0;
; #pragma unroll
;                 for (int bj = 0; bj < 2; ++bj) { const f32x4 v0 = acc[ai][bj][m][0], v1 = acc[ai][bj][m][1];
;                     float f[8] = {v0[0], v0[1], v0[2], v0[3], v1[0], v1[1], v1[2], v1[3]}; float g[8];
;                     unpack8(__builtin_nontemporal_load((const u32x4*)(gate + idx + bj * HALF)), g);
; #pragma unroll
;                     for (int e = 0; e < 8; ++e) f[e] *= g[e];
;                     if (!FIRST) { float p[8]; unpack8(*(const u32x4*)(merged + idx + bj * HALF), p);
; #pragma unroll
;                         for (int e = 0; e < 8; ++e) f[e] += p[e]; }
;                     *(u32x4*)(merged + idx + bj * HALF) = pack8(f); } }
	v_lshlrev_b32_e32 v128, 16, v214
	v_and_b32_e32 v129, 0xffff0000, v214
	v_lshlrev_b32_e32 v130, 16, v215
	v_and_b32_e32 v131, 0xffff0000, v215
	v_lshlrev_b32_e32 v230, 16, v216
	v_and_b32_e32 v231, 0xffff0000, v216
	v_lshlrev_b32_e32 v232, 16, v217
	v_and_b32_e32 v233, 0xffff0000, v217
	v_lshlrev_b32_e32 v148, 16, v222
	v_and_b32_e32 v149, 0xffff0000, v222
	v_lshlrev_b32_e32 v150, 16, v223
	v_and_b32_e32 v151, 0xffff0000, v223
	v_lshlrev_b32_e32 v200, 16, v224
	v_and_b32_e32 v201, 0xffff0000, v224
	v_lshlrev_b32_e32 v202, 16, v225
	v_and_b32_e32 v203, 0xffff0000, v225
	v_fmac_f32_e32 v148, v84, v128
	v_fmac_f32_e32 v149, v85, v129
	v_fmac_f32_e32 v150, v86, v130
	v_fmac_f32_e32 v151, v87, v131
	v_fmac_f32_e32 v200, v76, v230
	v_fmac_f32_e32 v201, v77, v231
	v_fmac_f32_e32 v202, v78, v232
	v_fmac_f32_e32 v203, v79, v233
	v_cvt_pk_bf16_f32 v214, v148, v149
	v_cvt_pk_bf16_f32 v215, v150, v151
	v_cvt_pk_bf16_f32 v216, v200, v201
	v_cvt_pk_bf16_f32 v217, v202, v203
	global_store_dwordx4 v243, v[214:217], s[10:11]
	v_lshlrev_b32_e32 v128, 16, v218
	v_and_b32_e32 v129, 0xffff0000, v218
	v_lshlrev_b32_e32 v130, 16, v219
	v_and_b32_e32 v131, 0xffff0000, v219
	v_lshlrev_b32_e32 v230, 16, v220
	v_and_b32_e32 v231, 0xffff0000, v220
	v_lshlrev_b32_e32 v232, 16, v221
	v_and_b32_e32 v233, 0xffff0000, v221
	v_lshlrev_b32_e32 v148, 16, v226
	v_and_b32_e32 v149, 0xffff0000, v226
	v_lshlrev_b32_e32 v150, 16, v227
	v_and_b32_e32 v151, 0xffff0000, v227
	v_lshlrev_b32_e32 v200, 16, v228
	v_and_b32_e32 v201, 0xffff0000, v228
	v_lshlrev_b32_e32 v202, 16, v229
	v_and_b32_e32 v203, 0xffff0000, v229
	v_fmac_f32_e32 v148, v68, v128
	v_fmac_f32_e32 v149, v69, v129
	v_fmac_f32_e32 v150, v70, v130
	v_fmac_f32_e32 v151, v71, v131
	v_fmac_f32_e32 v200, v64, v230
	v_fmac_f32_e32 v201, v65, v231
	v_fmac_f32_e32 v202, v66, v232
	v_fmac_f32_e32 v203, v67, v233
	v_cvt_pk_bf16_f32 v218, v148, v149
	v_cvt_pk_bf16_f32 v219, v150, v151
	v_cvt_pk_bf16_f32 v220, v200, v201
	v_cvt_pk_bf16_f32 v221, v202, v203
	global_store_dwordx4 v243, v[218:221], s[10:11] offset:256
	v_add_u32_e32 v243, 0x28000, v243
	global_load_dwordx4 v[214:217], v244, s[100:101] nt
	global_load_dwordx4 v[218:221], v244, s[100:101] offset:256 nt
	global_load_dwordx4 v[222:225], v242, s[10:11]
	global_load_dwordx4 v[226:229], v242, s[10:11] offset:256
	s_waitcnt vmcnt(18)
	v_lshlrev_b32_e32 v128, 16, v160
	v_and_b32_e32 v129, 0xffff0000, v160
	v_lshlrev_b32_e32 v130, 16, v161
	v_and_b32_e32 v131, 0xffff0000, v161
	v_lshlrev_b32_e32 v230, 16, v162
	v_and_b32_e32 v231, 0xffff0000, v162
	v_lshlrev_b32_e32 v232, 16, v163
	v_and_b32_e32 v233, 0xffff0000, v163
	v_lshlrev_b32_e32 v148, 16, v168
	v_and_b32_e32 v149, 0xffff0000, v168
	v_lshlrev_b32_e32 v150, 16, v169
	v_and_b32_e32 v151, 0xffff0000, v169
	v_lshlrev_b32_e32 v200, 16, v170
	v_and_b32_e32 v201, 0xffff0000, v170
	v_lshlrev_b32_e32 v202, 16, v171
	v_and_b32_e32 v203, 0xffff0000, v171
	v_fmac_f32_e32 v148, v60, v128
	v_fmac_f32_e32 v149, v61, v129
	v_fmac_f32_e32 v150, v62, v130
	v_fmac_f32_e32 v151, v63, v131
	v_fmac_f32_e32 v200, v56, v230
	v_fmac_f32_e32 v201, v57, v231
	v_fmac_f32_e32 v202, v58, v232
	v_fmac_f32_e32 v203, v59, v233
	v_cvt_pk_bf16_f32 v160, v148, v149
	v_cvt_pk_bf16_f32 v161, v150, v151
	v_cvt_pk_bf16_f32 v162, v200, v201
	v_cvt_pk_bf16_f32 v163, v202, v203
	global_store_dwordx4 v243, v[160:163], s[10:11]
	v_lshlrev_b32_e32 v128, 16, v164
	v_and_b32_e32 v129, 0xffff0000, v164
	v_lshlrev_b32_e32 v130, 16, v165
	v_and_b32_e32 v131, 0xffff0000, v165
	v_lshlrev_b32_e32 v230, 16, v166
	v_and_b32_e32 v231, 0xffff0000, v166
	v_lshlrev_b32_e32 v232, 16, v167
	v_and_b32_e32 v233, 0xffff0000, v167
	v_lshlrev_b32_e32 v148, 16, v172
	v_and_b32_e32 v149, 0xffff0000, v172
	v_lshlrev_b32_e32 v150, 16, v173
	v_and_b32_e32 v151, 0xffff0000, v173
	v_lshlrev_b32_e32 v200, 16, v174
	v_and_b32_e32 v201, 0xffff0000, v174
	v_lshlrev_b32_e32 v202, 16, v175
	v_and_b32_e32 v203, 0xffff0000, v175
	v_fmac_f32_e32 v148, v48, v128
	v_fmac_f32_e32 v149, v49, v129
	v_fmac_f32_e32 v150, v50, v130
	v_fmac_f32_e32 v151, v51, v131
	v_fmac_f32_e32 v200, v40, v230
	v_fmac_f32_e32 v201, v41, v231
	v_fmac_f32_e32 v202, v42, v232
	v_fmac_f32_e32 v203, v43, v233
	v_cvt_pk_bf16_f32 v164, v148, v149
	v_cvt_pk_bf16_f32 v165, v150, v151
	v_cvt_pk_bf16_f32 v166, v200, v201
	v_cvt_pk_bf16_f32 v167, v202, v203
	global_store_dwordx4 v243, v[164:167], s[10:11] offset:256
	v_add_u32_e32 v243, 0x8000, v243
	s_waitcnt vmcnt(14)
; __device__ __forceinline__ void unpack8(const u32x4 w, float (&f)[8]) { f[0] = bflo(w.x); f[1] = bfhi(w.x); f[2] = bflo(w.y); f[3] = bfhi(w.y); f[4] = bflo(w.z); f[5] = bfhi(w.z); f[6] = bflo(w.w); f[7] = bfhi(w.w); }
; __device__ __forceinline__ u32x4 pack8(const float (&f)[8]) { u32x4 w; w.x = cvt_pk_bf16(f[0], f[1]); w.y = cvt_pk_bf16(f[2], f[3]); w.z = cvt_pk_bf16(f[4], f[5]); w.w = cvt_pk_bf16(f[6], f[7]); return w; }
;     __device__ __forceinline__ void operator()(const f32x4 (&acc)[2][2][4][2], const Unit& u, int wr, int wc, int fr, int fq) const {
;     ...
;             for (int m = 0; m < 4; ++m) { const size_t idx = (size_t)(row0 + ai * HALF + m * 16) * 1024 + col0;
; #pragma unroll
;                 for (int bj = 0; bj < 2; ++bj) { const f32x4 v0 = acc[ai][bj][m][0], v1 = acc[ai][bj][m][1];
;                     float f[8] = {v0[0], v0[1], v0[2], v0[3], v1[0], v1[1], v1[2], v1[3]}; float g[8];
;                     unpack8(__builtin_nontemporal_load((const u32x4*)(gate + idx + bj * HALF)), g);
; #pragma unroll
;                     for (int e = 0; e < 8; ++e) f[e] *= g[e];
;                     if (!FIRST) { float p[8]; unpack8(*(const u32x4*)(merged + idx + bj * HALF), p);
; #pragma unroll
;                         for (int e = 0; e < 8; ++e) f[e] += p[e]; }
;                     *(u32x4*)(merged + idx + bj * HALF) = pack8(f); } }
	v_lshlrev_b32_e32 v128, 16, v176
	v_and_b32_e32 v129, 0xffff0000, v176
	v_lshlrev_b32_e32 v130, 16, v177
	v_and_b32_e32 v131, 0xffff0000, v177
	v_lshlrev_b32_e32 v230, 16, v178
	v_and_b32_e32 v231, 0xffff0000, v178
	v_lshlrev_b32_e32 v232, 16, v179
	v_and_b32_e32 v233, 0xffff0000, v179
	v_lshlrev_b32_e32 v148, 16, v184
	v_and_b32_e32 v149, 0xffff0000, v184
	v_lshlrev_b32_e32 v150, 16, v185
	v_and_b32_e32 v151, 0xffff0000, v185
	v_lshlrev_b32_e32 v200, 16, v186
	v_and_b32_e32 v201, 0xffff0000, v186
	v_lshlrev_b32_e32 v202, 16, v187
	v_and_b32_e32 v203, 0xffff0000, v187
	v_fmac_f32_e32 v148, v52, v128
	v_fmac_f32_e32 v149, v53, v129
	v_fmac_f32_e32 v150, v54, v130
	v_fmac_f32_e32 v151, v55, v131
	v_fmac_f32_e32 v200, v44, v230
	v_fmac_f32_e32 v201, v45, v231
	v_fmac_f32_e32 v202, v46, v232
	v_fmac_f32_e32 v203, v47, v233
	v_cvt_pk_bf16_f32 v176, v148, v149
	v_cvt_pk_bf16_f32 v177, v150, v151
	v_cvt_pk_bf16_f32 v178, v200, v201
	v_cvt_pk_bf16_f32 v179, v202, v203
	global_store_dwordx4 v243, v[176:179], s[10:11]
	v_lshlrev_b32_e32 v128, 16, v180
	v_and_b32_e32 v129, 0xffff0000, v180
	v_lshlrev_b32_e32 v130, 16, v181
	v_and_b32_e32 v131, 0xffff0000, v181
	v_lshlrev_b32_e32 v230, 16, v182
	v_and_b32_e32 v231, 0xffff0000, v182
	v_lshlrev_b32_e32 v232, 16, v183
	v_and_b32_e32 v233, 0xffff0000, v183
	v_lshlrev_b32_e32 v148, 16, v188
	v_and_b32_e32 v149, 0xffff0000, v188
	v_lshlrev_b32_e32 v150, 16, v189
	v_and_b32_e32 v151, 0xffff0000, v189
	v_lshlrev_b32_e32 v200, 16, v190
	v_and_b32_e32 v201, 0xffff0000, v190
	v_lshlrev_b32_e32 v202, 16, v191
	v_and_b32_e32 v203, 0xffff0000, v191
	v_fmac_f32_e32 v148, v32, v128
	v_fmac_f32_e32 v149, v33, v129
	v_fmac_f32_e32 v150, v34, v130
	v_fmac_f32_e32 v151, v35, v131
	v_fmac_f32_e32 v200, v24, v230
	v_fmac_f32_e32 v201, v25, v231
	v_fmac_f32_e32 v202, v26, v232
	v_fmac_f32_e32 v203, v27, v233
	v_cvt_pk_bf16_f32 v180, v148, v149
	v_cvt_pk_bf16_f32 v181, v150, v151
	v_cvt_pk_bf16_f32 v182, v200, v201
	v_cvt_pk_bf16_f32 v183, v202, v203
	global_store_dwordx4 v243, v[180:183], s[10:11] offset:256
	v_add_u32_e32 v243, 0x8000, v243
	s_waitcnt vmcnt(10)
	v_lshlrev_b32_e32 v128, 16, v192
	v_and_b32_e32 v129, 0xffff0000, v192
	v_lshlrev_b32_e32 v130, 16, v193
	v_and_b32_e32 v131, 0xffff0000, v193
	v_lshlrev_b32_e32 v230, 16, v194
	v_and_b32_e32 v231, 0xffff0000, v194
	v_lshlrev_b32_e32 v232, 16, v195
	v_and_b32_e32 v233, 0xffff0000, v195
	v_lshlrev_b32_e32 v148, 16, v206
	v_and_b32_e32 v149, 0xffff0000, v206
	v_lshlrev_b32_e32 v150, 16, v207
	v_and_b32_e32 v151, 0xffff0000, v207
	v_lshlrev_b32_e32 v200, 16, v208
	v_and_b32_e32 v201, 0xffff0000, v208
	v_lshlrev_b32_e32 v202, 16, v209
	v_and_b32_e32 v203, 0xffff0000, v209
	v_fmac_f32_e32 v148, v36, v128
	v_fmac_f32_e32 v149, v37, v129
	v_fmac_f32_e32 v150, v38, v130
	v_fmac_f32_e32 v151, v39, v131
	v_fmac_f32_e32 v200, v28, v230
	v_fmac_f32_e32 v201, v29, v231
	v_fmac_f32_e32 v202, v30, v232
	v_fmac_f32_e32 v203, v31, v233
	v_cvt_pk_bf16_f32 v192, v148, v149
	v_cvt_pk_bf16_f32 v193, v150, v151
	v_cvt_pk_bf16_f32 v194, v200, v201
	v_cvt_pk_bf16_f32 v195, v202, v203
	global_store_dwordx4 v243, v[192:195], s[10:11]
	v_lshlrev_b32_e32 v128, 16, v196
	v_and_b32_e32 v129, 0xffff0000, v196
	v_lshlrev_b32_e32 v130, 16, v197
	v_and_b32_e32 v131, 0xffff0000, v197
	v_lshlrev_b32_e32 v230, 16, v198
	v_and_b32_e32 v231, 0xffff0000, v198
	v_lshlrev_b32_e32 v232, 16, v199
	v_and_b32_e32 v233, 0xffff0000, v199
	v_lshlrev_b32_e32 v148, 16, v210
	v_and_b32_e32 v149, 0xffff0000, v210
	v_lshlrev_b32_e32 v150, 16, v211
	v_and_b32_e32 v151, 0xffff0000, v211
	v_lshlrev_b32_e32 v200, 16, v212
	v_and_b32_e32 v201, 0xffff0000, v212
	v_lshlrev_b32_e32 v202, 16, v213
	v_and_b32_e32 v203, 0xffff0000, v213
	v_fmac_f32_e32 v148, v16, v128
	v_fmac_f32_e32 v149, v17, v129
	v_fmac_f32_e32 v150, v18, v130
	v_fmac_f32_e32 v151, v19, v131
	v_fmac_f32_e32 v200, v8, v230
	v_fmac_f32_e32 v201, v9, v231
	v_fmac_f32_e32 v202, v10, v232
	v_fmac_f32_e32 v203, v11, v233
	v_cvt_pk_bf16_f32 v196, v148, v149
	v_cvt_pk_bf16_f32 v197, v150, v151
	v_cvt_pk_bf16_f32 v198, v200, v201
	v_cvt_pk_bf16_f32 v199, v202, v203
	global_store_dwordx4 v243, v[196:199], s[10:11] offset:256
	v_add_u32_e32 v243, 0x8000, v243
	s_waitcnt vmcnt(6)
	v_lshlrev_b32_e32 v128, 16, v214
	v_and_b32_e32 v129, 0xffff0000, v214
	v_lshlrev_b32_e32 v130, 16, v215
	v_and_b32_e32 v131, 0xffff0000, v215
	v_lshlrev_b32_e32 v230, 16, v216
	v_and_b32_e32 v231, 0xffff0000, v216
	v_lshlrev_b32_e32 v232, 16, v217
	v_and_b32_e32 v233, 0xffff0000, v217
	v_lshlrev_b32_e32 v148, 16, v222
	v_and_b32_e32 v149, 0xffff0000, v222
	v_lshlrev_b32_e32 v150, 16, v223
	v_and_b32_e32 v151, 0xffff0000, v223
	v_lshlrev_b32_e32 v200, 16, v224
	v_and_b32_e32 v201, 0xffff0000, v224
	v_lshlrev_b32_e32 v202, 16, v225
	v_and_b32_e32 v203, 0xffff0000, v225
	v_fmac_f32_e32 v148, v20, v128
	v_fmac_f32_e32 v149, v21, v129
	v_fmac_f32_e32 v150, v22, v130
	v_fmac_f32_e32 v151, v23, v131
	v_fmac_f32_e32 v200, v12, v230
	v_fmac_f32_e32 v201, v13, v231
	v_fmac_f32_e32 v202, v14, v232
	v_fmac_f32_e32 v203, v15, v233
	v_cvt_pk_bf16_f32 v214, v148, v149
	v_cvt_pk_bf16_f32 v215, v150, v151
	v_cvt_pk_bf16_f32 v216, v200, v201
	v_cvt_pk_bf16_f32 v217, v202, v203
	global_store_dwordx4 v243, v[214:217], s[10:11]
	v_lshlrev_b32_e32 v128, 16, v218
	v_and_b32_e32 v129, 0xffff0000, v218
	v_lshlrev_b32_e32 v130, 16, v219
	v_and_b32_e32 v131, 0xffff0000, v219
	v_lshlrev_b32_e32 v230, 16, v220
	v_and_b32_e32 v231, 0xffff0000, v220
	v_lshlrev_b32_e32 v232, 16, v221
	v_and_b32_e32 v233, 0xffff0000, v221
	v_lshlrev_b32_e32 v148, 16, v226
	v_and_b32_e32 v149, 0xffff0000, v226
	v_lshlrev_b32_e32 v150, 16, v227
	v_and_b32_e32 v151, 0xffff0000, v227
	v_lshlrev_b32_e32 v200, 16, v228
	v_and_b32_e32 v201, 0xffff0000, v228
	v_lshlrev_b32_e32 v202, 16, v229
	v_and_b32_e32 v203, 0xffff0000, v229
	v_fmac_f32_e32 v148, v4, v128
	v_fmac_f32_e32 v149, v5, v129
	v_fmac_f32_e32 v150, v6, v130
	v_fmac_f32_e32 v151, v7, v131
	v_fmac_f32_e32 v200, v0, v230
	v_fmac_f32_e32 v201, v1, v231
	v_fmac_f32_e32 v202, v2, v232
	v_fmac_f32_e32 v203, v3, v233
	v_cvt_pk_bf16_f32 v218, v148, v149
	v_cvt_pk_bf16_f32 v219, v150, v151
	v_cvt_pk_bf16_f32 v220, v200, v201
	v_cvt_pk_bf16_f32 v221, v202, v203
	global_store_dwordx4 v243, v[218:221], s[10:11] offset:256
.Lp3_done:
	s_andn2_b64 vcc, exec, s[0:1]
	s_mov_b64 s[0:1], -1
	s_cbranch_vccnz .LBB0_555
	s_andn2_b64 vcc, exec, s[8:9]
	s_cbranch_vccnz .LBB0_554
	s_barrier
	s_branch .LBB0_554

; __device__ __forceinline__ void unpack8(const u32x4 w, float (&f)[8]) { f[0] = bflo(w.x); f[1] = bfhi(w.x); f[2] = bflo(w.y); f[3] = bfhi(w.y); f[4] = bflo(w.z); f[5] = bfhi(w.z); f[6] = bflo(w.w); f[7] = bfhi(w.w); }
;     __device__ __forceinline__ void operator()(const f32x4 (&acc)[2][2][4][2], const Unit& u, int wr, int wc, int fr, int fq) const {
;         const int row0 = u.pm * BM + wr * 64 + fr, col0 = u.pn * BM + wc * 32 + 8 * fq;
; #pragma unroll
;         for (int ai = 0; ai < 2; ++ai)
; #pragma unroll
;             for (int m = 0; m < 4; ++m) { const size_t idx = (size_t)(row0 + ai * HALF + m * 16) * 1024 + col0;
; #pragma unroll
;                 for (int bj = 0; bj < 2; ++bj) { float h[8]; unpack8(__builtin_nontemporal_load((const u32x4*)(h1b + idx + bj * HALF)), h);
;                     const f32x4 a0 = acc[ai][bj][m][0], a1 = acc[ai][bj][m][1];
;                     __builtin_nontemporal_store(((f32x4){h[0] + a0[0], h[1] + a0[1], h[2] + a0[2], h[3] + a0[3]}), (f32x4*)(out + idx + bj * HALF));
;                     __builtin_nontemporal_store(((f32x4){h[4] + a1[0], h[5] + a1[1], h[6] + a1[2], h[7] + a1[3]}), (f32x4*)(out + idx + bj * HALF + 4)); } }
.LBB0_816:
	v_lshl_add_u32 v232, s28, 8, v150
	v_lshl_or_b32 v233, s47, 8, v152
	v_lshl_add_u32 v232, v232, 10, v233
	v_lshlrev_b32_e32 v233, 2, v232
	v_lshlrev_b32_e32 v232, 1, v232
	global_load_dwordx4 v[156:159], v232, s[8:9] nt
	global_load_dwordx4 v[160:163], v232, s[8:9] offset:256 nt
	v_add_u32_e32 v232, 0x8000, v232
	global_load_dwordx4 v[164:167], v232, s[8:9] nt
	global_load_dwordx4 v[168:171], v232, s[8:9] offset:256 nt
	v_add_u32_e32 v232, 0x8000, v232
	global_load_dwordx4 v[172:175], v232, s[8:9] nt
	global_load_dwordx4 v[176:179], v232, s[8:9] offset:256 nt
	v_add_u32_e32 v232, 0x8000, v232
	global_load_dwordx4 v[180:183], v232, s[8:9] nt
	global_load_dwordx4 v[184:187], v232, s[8:9] offset:256 nt
	v_add_u32_e32 v232, 0x28000, v232
	global_load_dwordx4 v[188:191], v232, s[8:9] nt
	global_load_dwordx4 v[192:195], v232, s[8:9] offset:256 nt
	v_add_u32_e32 v232, 0x8000, v232
	global_load_dwordx4 v[196:199], v232, s[8:9] nt
	global_load_dwordx4 v[200:203], v232, s[8:9] offset:256 nt
	v_add_u32_e32 v232, 0x8000, v232
	global_load_dwordx4 v[204:207], v232, s[8:9] nt
	global_load_dwordx4 v[208:211], v232, s[8:9] offset:256 nt
	v_add_u32_e32 v232, 0x8000, v232
	global_load_dwordx4 v[212:215], v232, s[8:9] nt
	global_load_dwordx4 v[216:219], v232, s[8:9] offset:256 nt
	s_waitcnt vmcnt(14)
	v_lshlrev_b32_e32 v224, 16, v156
	v_and_b32_e32 v225, 0xffff0000, v156
	v_lshlrev_b32_e32 v226, 16, v157
	v_and_b32_e32 v227, 0xffff0000, v157
	v_lshlrev_b32_e32 v228, 16, v158
	v_and_b32_e32 v229, 0xffff0000, v158
	v_lshlrev_b32_e32 v230, 16, v159
	v_and_b32_e32 v231, 0xffff0000, v159
	v_pk_add_f32 v[124:125], v[124:125], v[224:225]
	v_pk_add_f32 v[126:127], v[126:127], v[226:227]
	v_pk_add_f32 v[120:121], v[120:121], v[228:229]
	v_pk_add_f32 v[122:123], v[122:123], v[230:231]
	global_store_dwordx4 v233, v[124:127], s[50:51] nt
	global_store_dwordx4 v233, v[120:123], s[50:51] offset:16 nt
	v_lshlrev_b32_e32 v224, 16, v160
	v_and_b32_e32 v225, 0xffff0000, v160
	v_lshlrev_b32_e32 v226, 16, v161
	v_and_b32_e32 v227, 0xffff0000, v161
	v_lshlrev_b32_e32 v228, 16, v162
	v_and_b32_e32 v229, 0xffff0000, v162
	v_lshlrev_b32_e32 v230, 16, v163
	v_and_b32_e32 v231, 0xffff0000, v163
	v_pk_add_f32 v[116:117], v[116:117], v[224:225]
	v_pk_add_f32 v[118:119], v[118:119], v[226:227]
	v_pk_add_f32 v[112:113], v[112:113], v[228:229]
	v_pk_add_f32 v[114:115], v[114:115], v[230:231]
	global_store_dwordx4 v233, v[116:119], s[50:51] offset:512 nt
	global_store_dwordx4 v233, v[112:115], s[50:51] offset:528 nt
	v_add_u32_e32 v233, 0x10000, v233
	s_waitcnt vmcnt(16)
	v_lshlrev_b32_e32 v224, 16, v164
	v_and_b32_e32 v225, 0xffff0000, v164
	v_lshlrev_b32_e32 v226, 16, v165
	v_and_b32_e32 v227, 0xffff0000, v165
	v_lshlrev_b32_e32 v228, 16, v166
	v_and_b32_e32 v229, 0xffff0000, v166
	v_lshlrev_b32_e32 v230, 16, v167
	v_and_b32_e32 v231, 0xffff0000, v167
	v_pk_add_f32 v[108:109], v[108:109], v[224:225]
	v_pk_add_f32 v[110:111], v[110:111], v[226:227]
	v_pk_add_f32 v[104:105], v[104:105], v[228:229]
	v_pk_add_f32 v[106:107], v[106:107], v[230:231]
	global_store_dwordx4 v233, v[108:111], s[50:51] nt
	global_store_dwordx4 v233, v[104:107], s[50:51] offset:16 nt
	v_lshlrev_b32_e32 v224, 16, v168
	v_and_b32_e32 v225, 0xffff0000, v168
	v_lshlrev_b32_e32 v226, 16, v169
	v_and_b32_e32 v227, 0xffff0000, v169
	v_lshlrev_b32_e32 v228, 16, v170
	v_and_b32_e32 v229, 0xffff0000, v170
	v_lshlrev_b32_e32 v230, 16, v171
	v_and_b32_e32 v231, 0xffff0000, v171
	v_pk_add_f32 v[100:101], v[100:101], v[224:225]
	v_pk_add_f32 v[102:103], v[102:103], v[226:227]
	v_pk_add_f32 v[96:97], v[96:97], v[228:229]
	v_pk_add_f32 v[98:99], v[98:99], v[230:231]
	global_store_dwordx4 v233, v[100:103], s[50:51] offset:512 nt
	global_store_dwordx4 v233, v[96:99], s[50:51] offset:528 nt
	v_add_u32_e32 v233, 0x10000, v233
	s_waitcnt vmcnt(18)
	v_lshlrev_b32_e32 v224, 16, v172
	v_and_b32_e32 v225, 0xffff0000, v172
	v_lshlrev_b32_e32 v226, 16, v173
	v_and_b32_e32 v227, 0xffff0000, v173
	v_lshlrev_b32_e32 v228, 16, v174
	v_and_b32_e32 v229, 0xffff0000, v174
	v_lshlrev_b32_e32 v230, 16, v175
	v_and_b32_e32 v231, 0xffff0000, v175
	v_pk_add_f32 v[92:93], v[92:93], v[224:225]
	v_pk_add_f32 v[94:95], v[94:95], v[226:227]
	v_pk_add_f32 v[88:89], v[88:89], v[228:229]
	v_pk_add_f32 v[90:91], v[90:91], v[230:231]
	global_store_dwordx4 v233, v[92:95], s[50:51] nt
	global_store_dwordx4 v233, v[88:91], s[50:51] offset:16 nt
	v_lshlrev_b32_e32 v224, 16, v176
	v_and_b32_e32 v225, 0xffff0000, v176
	v_lshlrev_b32_e32 v226, 16, v177
	v_and_b32_e32 v227, 0xffff0000, v177
	v_lshlrev_b32_e32 v228, 16, v178
	v_and_b32_e32 v229, 0xffff0000, v178
	v_lshlrev_b32_e32 v230, 16, v179
	v_and_b32_e32 v231, 0xffff0000, v179
	v_pk_add_f32 v[84:85], v[84:85], v[224:225]
	v_pk_add_f32 v[86:87], v[86:87], v[226:227]
	v_pk_add_f32 v[80:81], v[80:81], v[228:229]
	v_pk_add_f32 v[82:83], v[82:83], v[230:231]
	global_store_dwordx4 v233, v[84:87], s[50:51] offset:512 nt
	global_store_dwordx4 v233, v[80:83], s[50:51] offset:528 nt
	v_add_u32_e32 v233, 0x10000, v233
	s_waitcnt vmcnt(20)
; __device__ __forceinline__ void unpack8(const u32x4 w, float (&f)[8]) { f[0] = bflo(w.x); f[1] = bfhi(w.x); f[2] = bflo(w.y); f[3] = bfhi(w.y); f[4] = bflo(w.z); f[5] = bfhi(w.z); f[6] = bflo(w.w); f[7] = bfhi(w.w); }
;     __device__ __forceinline__ void operator()(const f32x4 (&acc)[2][2][4][2], const Unit& u, int wr, int wc, int fr, int fq) const {
;         const int row0 = u.pm * BM + wr * 64 + fr, col0 = u.pn * BM + wc * 32 + 8 * fq;
; #pragma unroll
;         for (int ai = 0; ai < 2; ++ai)
; #pragma unroll
;             for (int m = 0; m < 4; ++m) { const size_t idx = (size_t)(row0 + ai * HALF + m * 16) * 1024 + col0;
; #pragma unroll
;                 for (int bj = 0; bj < 2; ++bj) { float h[8]; unpack8(__builtin_nontemporal_load((const u32x4*)(h1b + idx + bj * HALF)), h);
;                     const f32x4 a0 = acc[ai][bj][m][0], a1 = acc[ai][bj][m][1];
;                     __builtin_nontemporal_store(((f32x4){h[0] + a0[0], h[1] + a0[1], h[2] + a0[2], h[3] + a0[3]}), (f32x4*)(out + idx + bj * HALF));
;                     __builtin_nontemporal_store(((f32x4){h[4] + a1[0], h[5] + a1[1], h[6] + a1[2], h[7] + a1[3]}), (f32x4*)(out + idx + bj * HALF + 4)); } }
	v_lshlrev_b32_e32 v224, 16, v180
	v_and_b32_e32 v225, 0xffff0000, v180
	v_lshlrev_b32_e32 v226, 16, v181
	v_and_b32_e32 v227, 0xffff0000, v181
	v_lshlrev_b32_e32 v228, 16, v182
	v_and_b32_e32 v229, 0xffff0000, v182
	v_lshlrev_b32_e32 v230, 16, v183
	v_and_b32_e32 v231, 0xffff0000, v183
	v_pk_add_f32 v[76:77], v[76:77], v[224:225]
	v_pk_add_f32 v[78:79], v[78:79], v[226:227]
	v_pk_add_f32 v[72:73], v[72:73], v[228:229]
	v_pk_add_f32 v[74:75], v[74:75], v[230:231]
	global_store_dwordx4 v233, v[76:79], s[50:51] nt
	global_store_dwordx4 v233, v[72:75], s[50:51] offset:16 nt
	v_lshlrev_b32_e32 v224, 16, v184
	v_and_b32_e32 v225, 0xffff0000, v184
	v_lshlrev_b32_e32 v226, 16, v185
	v_and_b32_e32 v227, 0xffff0000, v185
	v_lshlrev_b32_e32 v228, 16, v186
	v_and_b32_e32 v229, 0xffff0000, v186
	v_lshlrev_b32_e32 v230, 16, v187
	v_and_b32_e32 v231, 0xffff0000, v187
	v_pk_add_f32 v[68:69], v[68:69], v[224:225]
	v_pk_add_f32 v[70:71], v[70:71], v[226:227]
	v_pk_add_f32 v[64:65], v[64:65], v[228:229]
	v_pk_add_f32 v[66:67], v[66:67], v[230:231]
	global_store_dwordx4 v233, v[68:71], s[50:51] offset:512 nt
	global_store_dwordx4 v233, v[64:67], s[50:51] offset:528 nt
	v_add_u32_e32 v233, 0x50000, v233
	s_waitcnt vmcnt(22)
	v_lshlrev_b32_e32 v224, 16, v188
	v_and_b32_e32 v225, 0xffff0000, v188
	v_lshlrev_b32_e32 v226, 16, v189
	v_and_b32_e32 v227, 0xffff0000, v189
	v_lshlrev_b32_e32 v228, 16, v190
	v_and_b32_e32 v229, 0xffff0000, v190
	v_lshlrev_b32_e32 v230, 16, v191
	v_and_b32_e32 v231, 0xffff0000, v191
	v_pk_add_f32 v[60:61], v[60:61], v[224:225]
	v_pk_add_f32 v[62:63], v[62:63], v[226:227]
	v_pk_add_f32 v[56:57], v[56:57], v[228:229]
	v_pk_add_f32 v[58:59], v[58:59], v[230:231]
	global_store_dwordx4 v233, v[60:63], s[50:51] nt
	global_store_dwordx4 v233, v[56:59], s[50:51] offset:16 nt
	v_lshlrev_b32_e32 v224, 16, v192
	v_and_b32_e32 v225, 0xffff0000, v192
	v_lshlrev_b32_e32 v226, 16, v193
	v_and_b32_e32 v227, 0xffff0000, v193
	v_lshlrev_b32_e32 v228, 16, v194
	v_and_b32_e32 v229, 0xffff0000, v194
	v_lshlrev_b32_e32 v230, 16, v195
	v_and_b32_e32 v231, 0xffff0000, v195
	v_pk_add_f32 v[52:53], v[52:53], v[224:225]
	v_pk_add_f32 v[54:55], v[54:55], v[226:227]
	v_pk_add_f32 v[48:49], v[48:49], v[228:229]
	v_pk_add_f32 v[50:51], v[50:51], v[230:231]
	global_store_dwordx4 v233, v[52:55], s[50:51] offset:512 nt
	global_store_dwordx4 v233, v[48:51], s[50:51] offset:528 nt
	v_add_u32_e32 v233, 0x10000, v233
	s_waitcnt vmcnt(24)
	v_lshlrev_b32_e32 v224, 16, v196
	v_and_b32_e32 v225, 0xffff0000, v196
	v_lshlrev_b32_e32 v226, 16, v197
	v_and_b32_e32 v227, 0xffff0000, v197
	v_lshlrev_b32_e32 v228, 16, v198
	v_and_b32_e32 v229, 0xffff0000, v198
	v_lshlrev_b32_e32 v230, 16, v199
	v_and_b32_e32 v231, 0xffff0000, v199
	v_pk_add_f32 v[44:45], v[44:45], v[224:225]
	v_pk_add_f32 v[46:47], v[46:47], v[226:227]
	v_pk_add_f32 v[40:41], v[40:41], v[228:229]
	v_pk_add_f32 v[42:43], v[42:43], v[230:231]
	global_store_dwordx4 v233, v[44:47], s[50:51] nt
	global_store_dwordx4 v233, v[40:43], s[50:51] offset:16 nt
	v_lshlrev_b32_e32 v224, 16, v200
	v_and_b32_e32 v225, 0xffff0000, v200
	v_lshlrev_b32_e32 v226, 16, v201
	v_and_b32_e32 v227, 0xffff0000, v201
	v_lshlrev_b32_e32 v228, 16, v202
	v_and_b32_e32 v229, 0xffff0000, v202
	v_lshlrev_b32_e32 v230, 16, v203
	v_and_b32_e32 v231, 0xffff0000, v203
	v_pk_add_f32 v[36:37], v[36:37], v[224:225]
	v_pk_add_f32 v[38:39], v[38:39], v[226:227]
	v_pk_add_f32 v[32:33], v[32:33], v[228:229]
	v_pk_add_f32 v[34:35], v[34:35], v[230:231]
	global_store_dwordx4 v233, v[36:39], s[50:51] offset:512 nt
	global_store_dwordx4 v233, v[32:35], s[50:51] offset:528 nt
	v_add_u32_e32 v233, 0x10000, v233
	s_waitcnt vmcnt(26)
	v_lshlrev_b32_e32 v224, 16, v204
	v_and_b32_e32 v225, 0xffff0000, v204
	v_lshlrev_b32_e32 v226, 16, v205
	v_and_b32_e32 v227, 0xffff0000, v205
	v_lshlrev_b32_e32 v228, 16, v206
	v_and_b32_e32 v229, 0xffff0000, v206
	v_lshlrev_b32_e32 v230, 16, v207
	v_and_b32_e32 v231, 0xffff0000, v207
	v_pk_add_f32 v[28:29], v[28:29], v[224:225]
	v_pk_add_f32 v[30:31], v[30:31], v[226:227]
	v_pk_add_f32 v[24:25], v[24:25], v[228:229]
	v_pk_add_f32 v[26:27], v[26:27], v[230:231]
	global_store_dwordx4 v233, v[28:31], s[50:51] nt
	global_store_dwordx4 v233, v[24:27], s[50:51] offset:16 nt
	v_lshlrev_b32_e32 v224, 16, v208
	v_and_b32_e32 v225, 0xffff0000, v208
	v_lshlrev_b32_e32 v226, 16, v209
	v_and_b32_e32 v227, 0xffff0000, v209
	v_lshlrev_b32_e32 v228, 16, v210
	v_and_b32_e32 v229, 0xffff0000, v210
	v_lshlrev_b32_e32 v230, 16, v211
	v_and_b32_e32 v231, 0xffff0000, v211
	v_pk_add_f32 v[20:21], v[20:21], v[224:225]
	v_pk_add_f32 v[22:23], v[22:23], v[226:227]
	v_pk_add_f32 v[16:17], v[16:17], v[228:229]
	v_pk_add_f32 v[18:19], v[18:19], v[230:231]
	global_store_dwordx4 v233, v[20:23], s[50:51] offset:512 nt
	global_store_dwordx4 v233, v[16:19], s[50:51] offset:528 nt
	v_add_u32_e32 v233, 0x10000, v233
	s_waitcnt vmcnt(28)
	v_lshlrev_b32_e32 v224, 16, v212
	v_and_b32_e32 v225, 0xffff0000, v212
	v_lshlrev_b32_e32 v226, 16, v213
	v_and_b32_e32 v227, 0xffff0000, v213
	v_lshlrev_b32_e32 v228, 16, v214
	v_and_b32_e32 v229, 0xffff0000, v214
	v_lshlrev_b32_e32 v230, 16, v215
	v_and_b32_e32 v231, 0xffff0000, v215
	v_pk_add_f32 v[12:13], v[12:13], v[224:225]
	v_pk_add_f32 v[14:15], v[14:15], v[226:227]
	v_pk_add_f32 v[8:9], v[8:9], v[228:229]
	v_pk_add_f32 v[10:11], v[10:11], v[230:231]
	global_store_dwordx4 v233, v[12:15], s[50:51] nt
	global_store_dwordx4 v233, v[8:11], s[50:51] offset:16 nt
	v_lshlrev_b32_e32 v224, 16, v216
	v_and_b32_e32 v225, 0xffff0000, v216
	v_lshlrev_b32_e32 v226, 16, v217
	v_and_b32_e32 v227, 0xffff0000, v217
	v_lshlrev_b32_e32 v228, 16, v218
	v_and_b32_e32 v229, 0xffff0000, v218
	v_lshlrev_b32_e32 v230, 16, v219
	v_and_b32_e32 v231, 0xffff0000, v219
	v_pk_add_f32 v[4:5], v[4:5], v[224:225]
	v_pk_add_f32 v[6:7], v[6:7], v[226:227]
	v_pk_add_f32 v[0:1], v[0:1], v[228:229]
	v_pk_add_f32 v[2:3], v[2:3], v[230:231]
	global_store_dwordx4 v233, v[4:7], s[50:51] offset:512 nt
	global_store_dwordx4 v233, v[0:3], s[50:51] offset:528 nt
	s_andn2_b64 vcc, exec, s[0:1]
	s_mov_b64 s[0:1], -1
	s_cbranch_vccnz .LBB0_805
	s_andn2_b64 vcc, exec, s[4:5]
	s_cbranch_vccnz .LBB0_804
	s_barrier
	s_branch .LBB0_804

; #define LAS __attribute__((address_space(3)))
; __global__ void __launch_bounds__(512) mk_fwd(Args a) {
;     extern __shared__ __attribute__((aligned(16))) unsigned char lds_raw[];
;     cg::grid_group grid = cg::this_grid();
;     LAS unsigned char* lds = (LAS unsigned char*)lds_raw;
;     const int tid = threadIdx.x, G = gridDim.x, blk = blockIdx.x;
	.amdhsa_kernel _Z6mk_fwd4Args
		.amdhsa_group_segment_fixed_size 0
		.amdhsa_private_segment_fixed_size 0
		.amdhsa_kernarg_size 392
		.amdhsa_user_sgpr_count 2
		.amdhsa_user_sgpr_dispatch_ptr 0
		.amdhsa_user_sgpr_queue_ptr 0
		.amdhsa_user_sgpr_kernarg_segment_ptr 1
		.amdhsa_user_sgpr_dispatch_id 0
		.amdhsa_user_sgpr_kernarg_preload_length 0
		.amdhsa_user_sgpr_kernarg_preload_offset 0
		.amdhsa_user_sgpr_private_segment_size 0
		.amdhsa_uses_dynamic_stack 0
		.amdhsa_enable_private_segment 0
		.amdhsa_system_sgpr_workgroup_id_x 1
		.amdhsa_system_sgpr_workgroup_id_y 0
		.amdhsa_system_sgpr_workgroup_id_z 0
		.amdhsa_system_sgpr_workgroup_info 0
		.amdhsa_system_vgpr_workitem_id 2
		.amdhsa_next_free_vgpr 247
		.amdhsa_next_free_sgpr 102
		.amdhsa_accum_offset 248
		.amdhsa_reserve_vcc 1
		.amdhsa_float_round_mode_32 0
		.amdhsa_float_round_mode_16_64 0
		.amdhsa_float_denorm_mode_32 3
		.amdhsa_float_denorm_mode_16_64 3
		.amdhsa_dx10_clamp 1
		.amdhsa_ieee_mode 1
		.amdhsa_fp16_overflow 0
		.amdhsa_tg_split 0
		.amdhsa_exception_fp_ieee_invalid_op 0
		.amdhsa_exception_fp_denorm_src 0
		.amdhsa_exception_fp_ieee_div_zero 0
		.amdhsa_exception_fp_ieee_overflow 0
		.amdhsa_exception_fp_ieee_underflow 0
		.amdhsa_exception_fp_ieee_inexact 0
		.amdhsa_exception_int_div_zero 0
	.end_amdhsa_kernel

; __global__ void __launch_bounds__(512) mk_fwd(Args a) {
amdhsa.kernels:
  - .agpr_count:     0
    .args:
      - .offset:         0
        .size:           136
        .value_kind:     by_value
      - .offset:         136
        .size:           4
        .value_kind:     hidden_block_count_x
      - .offset:         140
        .size:           4
        .value_kind:     hidden_block_count_y
      - .offset:         144
        .size:           4
        .value_kind:     hidden_block_count_z
      - .offset:         148
        .size:           2
        .value_kind:     hidden_group_size_x
      - .offset:         150
        .size:           2
        .value_kind:     hidden_group_size_y
      - .offset:         152
        .size:           2
        .value_kind:     hidden_group_size_z
      - .offset:         154
        .size:           2
        .value_kind:     hidden_remainder_x
      - .offset:         156
        .size:           2
        .value_kind:     hidden_remainder_y
      - .offset:         158
        .size:           2
        .value_kind:     hidden_remainder_z
      - .offset:         176
        .size:           8
        .value_kind:     hidden_global_offset_x
      - .offset:         184
        .size:           8
        .value_kind:     hidden_global_offset_y
      - .offset:         192
        .size:           8
        .value_kind:     hidden_global_offset_z
      - .offset:         200
        .size:           2
        .value_kind:     hidden_grid_dims
      - .offset:         224
        .size:           8
        .value_kind:     hidden_multigrid_sync_arg
      - .offset:         256
        .size:           4
        .value_kind:     hidden_dynamic_lds_size
    .group_segment_fixed_size: 0
    .kernarg_segment_align: 8
    .kernarg_segment_size: 392
    .language:       OpenCL C
    .language_version:
      - 2
      - 0
    .max_flat_workgroup_size: 512
    .name:           _Z6mk_fwd4Args
    .private_segment_fixed_size: 0
    .sgpr_count:     108
    .sgpr_spill_count: 18
    .symbol:         _Z6mk_fwd4Args.kd
    .uniform_work_group_size: 1
    .uses_dynamic_stack: false
    .vgpr_count:     247
    .vgpr_spill_count: 0
    .wavefront_size: 64
